# forward substitution: right-hand-side rows read with paired strided LDS loads (ds_read2st64_b32), 16 instead of 32 per wave
# speedup vs baseline: 1.0055x; 1.0011x over previous
; #define LAS __attribute__((address_space(3)))
; __device__ __forceinline__ void phase_chunk_prep(const Params& p, LAS unsigned char* lds, int wave_s) {
;     ...
;         if (tid < 256) {
;             const int col = tid; float sol[64];
; #pragma unroll
;             for (int i = 0; i < 64; ++i) sol[i] = 0.f;
; #pragma unroll
;             for (int i = 0; i < 64; ++i) {
;                 float s0 = RHS[i * 256 + col], s1 = 0.f, s2 = 0.f, s3 = 0.f;
; #pragma unroll
;                 for (int j4 = 0; j4 < (i + 3) / 4; ++j4) { const f32x4 a = *(const LAS f32x4*)(AM + i * 64 + 4 * j4);
;                     s0 -= a.x * sol[4 * j4]; s1 -= a.y * sol[4 * j4 + 1]; s2 -= a.z * sol[4 * j4 + 2]; s3 -= a.w * sol[4 * j4 + 3]; }
;                 sol[i] = (s0 + s1) + (s2 + s3);
;             }
.Lcpstage_n_end:
	s_lshr_b32 s84, s24, 6
	v_mbcnt_lo_u32_b32 v32, -1, 0
	v_mbcnt_hi_u32_b32 v32, -1, v32
	v_and_b32_e32 v33, 15, v32
	v_lshrrev_b32_e32 v34, 4, v32
	s_lshl_b32 s85, s84, 7
	v_lshl_add_u32 v84, v33, 2, s85
	v_lshl_add_u32 v84, v34, 12, v84
	v_add_u32_e32 v84, 0xc800, v84
	v_lshlrev_b32_e32 v85, 8, v33
	v_lshl_add_u32 v85, v34, 4, v85
	v_add_u32_e32 v85, 0x8800, v85
	v_mul_u32_u24_e32 v86, 80, v33
	v_lshl_add_u32 v86, v34, 4, v86
	v_add_u32_e32 v86, 0x22600, v86
	v_add_u32_e32 v93, 64, v84
	ds_read2st64_b32 v[0:1], v84 offset0:0 offset1:4
	ds_read2st64_b32 v[2:3], v84 offset0:8 offset1:12
	ds_read2st64_b32 v[4:5], v84 offset0:64 offset1:68
	ds_read2st64_b32 v[6:7], v84 offset0:72 offset1:76
	ds_read2st64_b32 v[8:9], v84 offset0:128 offset1:132
	ds_read2st64_b32 v[10:11], v84 offset0:136 offset1:140
	ds_read2st64_b32 v[12:13], v84 offset0:192 offset1:196
	ds_read2st64_b32 v[14:15], v84 offset0:200 offset1:204
	ds_read2st64_b32 v[16:17], v93 offset0:0 offset1:4
	ds_read2st64_b32 v[18:19], v93 offset0:8 offset1:12
	ds_read2st64_b32 v[20:21], v93 offset0:64 offset1:68
	ds_read2st64_b32 v[22:23], v93 offset0:72 offset1:76
	ds_read2st64_b32 v[24:25], v93 offset0:128 offset1:132
	ds_read2st64_b32 v[26:27], v93 offset0:136 offset1:140
	ds_read2st64_b32 v[28:29], v93 offset0:192 offset1:196
	ds_read2st64_b32 v[30:31], v93 offset0:200 offset1:204
	ds_read_b128 v[148:151], v85 offset:4096
	ds_read_b128 v[152:155], v85 offset:8192
	ds_read_b128 v[156:159], v85 offset:8256
	ds_read_b128 v[160:163], v85 offset:12288
	ds_read_b128 v[164:167], v85 offset:12352
	ds_read_b128 v[168:171], v85 offset:12416
	s_cmp_lg_u32 s84, 0
	s_cbranch_scc1 .Lfm_not0
	v_mul_u32_u24_e32 v88, 0x1040, v34
	v_lshl_add_u32 v88, v33, 2, v88
	v_add_u32_e32 v88, 0x8800, v88
	ds_read_b32 v101, v88 offset:256
	ds_read_b32 v102, v88 offset:512
	ds_read_b32 v103, v88 offset:768
	ds_read_b32 v104, v88 offset:1024
	ds_read_b32 v105, v88 offset:1280
	ds_read_b32 v106, v88 offset:1536
	ds_read_b32 v107, v88 offset:1792
	ds_read_b32 v108, v88 offset:2048
	ds_read_b32 v109, v88 offset:2304
	ds_read_b32 v110, v88 offset:2560
	ds_read_b32 v111, v88 offset:2816
	ds_read_b32 v112, v88 offset:3072
	ds_read_b32 v113, v88 offset:3328
	ds_read_b32 v114, v88 offset:3584
	ds_read_b32 v115, v88 offset:3840
	v_mul_u32_u24_e32 v87, 0x500, v34
	v_lshl_add_u32 v87, v33, 2, v87
	v_add_u32_e32 v87, 0x22600, v87
	v_cmp_eq_u32_e32 vcc, 0, v33
	v_cmp_eq_u32_e64 s[86:87], 1, v33
	s_nop 0
	v_cndmask_b32_e64 v116, 0, 1.0, vcc
	v_cndmask_b32_e64 v117, 0, 1.0, s[86:87]
	v_cmp_eq_u32_e32 vcc, 2, v33
	v_cmp_eq_u32_e64 s[86:87], 3, v33
	s_nop 0
	v_cndmask_b32_e64 v118, 0, 1.0, vcc
	v_cndmask_b32_e64 v119, 0, 1.0, s[86:87]
	v_cmp_eq_u32_e32 vcc, 4, v33
	v_cmp_eq_u32_e64 s[86:87], 5, v33
	s_nop 0
	v_cndmask_b32_e64 v120, 0, 1.0, vcc
	v_cndmask_b32_e64 v121, 0, 1.0, s[86:87]
	v_cmp_eq_u32_e32 vcc, 6, v33
	v_cmp_eq_u32_e64 s[86:87], 7, v33
	s_nop 0
	v_cndmask_b32_e64 v122, 0, 1.0, vcc
	v_cndmask_b32_e64 v123, 0, 1.0, s[86:87]
	v_cmp_eq_u32_e32 vcc, 8, v33
	v_cmp_eq_u32_e64 s[86:87], 9, v33
	s_nop 0
	v_cndmask_b32_e64 v124, 0, 1.0, vcc
	v_cndmask_b32_e64 v125, 0, 1.0, s[86:87]
	v_cmp_eq_u32_e32 vcc, 10, v33
	v_cmp_eq_u32_e64 s[86:87], 11, v33
	s_nop 0
	v_cndmask_b32_e64 v126, 0, 1.0, vcc
	v_cndmask_b32_e64 v127, 0, 1.0, s[86:87]
	v_cmp_eq_u32_e32 vcc, 12, v33
	v_cmp_eq_u32_e64 s[86:87], 13, v33
	s_nop 0
	v_cndmask_b32_e64 v128, 0, 1.0, vcc
	v_cndmask_b32_e64 v129, 0, 1.0, s[86:87]
	v_cmp_eq_u32_e32 vcc, 14, v33
	v_cmp_eq_u32_e64 s[86:87], 15, v33
	s_nop 0
	v_cndmask_b32_e64 v130, 0, 1.0, vcc
	v_cndmask_b32_e64 v131, 0, 1.0, s[86:87]
	s_waitcnt lgkmcnt(0)
	v_fmac_f32_dpp v117, -v101, v116 row_newbcast:0 row_mask:0xf bank_mask:0xf
	v_fmac_f32_dpp v118, -v102, v116 row_newbcast:0 row_mask:0xf bank_mask:0xf
	v_fmac_f32_dpp v118, -v102, v117 row_newbcast:1 row_mask:0xf bank_mask:0xf
	v_fmac_f32_dpp v119, -v103, v116 row_newbcast:0 row_mask:0xf bank_mask:0xf
	v_fmac_f32_dpp v119, -v103, v117 row_newbcast:1 row_mask:0xf bank_mask:0xf
	v_fmac_f32_dpp v119, -v103, v118 row_newbcast:2 row_mask:0xf bank_mask:0xf
	v_mov_b32_e32 v92, 0
	v_fmac_f32_dpp v120, -v104, v116 row_newbcast:0 row_mask:0xf bank_mask:0xf
	v_fmac_f32_dpp v92, -v104, v117 row_newbcast:1 row_mask:0xf bank_mask:0xf
	v_fmac_f32_dpp v120, -v104, v118 row_newbcast:2 row_mask:0xf bank_mask:0xf
	v_fmac_f32_dpp v92, -v104, v119 row_newbcast:3 row_mask:0xf bank_mask:0xf
	v_add_f32_e32 v120, v120, v92
	v_mov_b32_e32 v92, 0
	v_fmac_f32_dpp v121, -v105, v116 row_newbcast:0 row_mask:0xf bank_mask:0xf
	v_fmac_f32_dpp v92, -v105, v117 row_newbcast:1 row_mask:0xf bank_mask:0xf
	v_fmac_f32_dpp v121, -v105, v118 row_newbcast:2 row_mask:0xf bank_mask:0xf
	v_fmac_f32_dpp v92, -v105, v119 row_newbcast:3 row_mask:0xf bank_mask:0xf
	v_fmac_f32_dpp v121, -v105, v120 row_newbcast:4 row_mask:0xf bank_mask:0xf
	v_add_f32_e32 v121, v121, v92
	v_mov_b32_e32 v92, 0
	v_fmac_f32_dpp v122, -v106, v116 row_newbcast:0 row_mask:0xf bank_mask:0xf
	v_fmac_f32_dpp v92, -v106, v117 row_newbcast:1 row_mask:0xf bank_mask:0xf
	v_fmac_f32_dpp v122, -v106, v118 row_newbcast:2 row_mask:0xf bank_mask:0xf
	v_fmac_f32_dpp v92, -v106, v119 row_newbcast:3 row_mask:0xf bank_mask:0xf
	v_fmac_f32_dpp v122, -v106, v120 row_newbcast:4 row_mask:0xf bank_mask:0xf
	v_fmac_f32_dpp v92, -v106, v121 row_newbcast:5 row_mask:0xf bank_mask:0xf
	v_add_f32_e32 v122, v122, v92
	v_mov_b32_e32 v92, 0
	v_fmac_f32_dpp v123, -v107, v116 row_newbcast:0 row_mask:0xf bank_mask:0xf
	v_fmac_f32_dpp v92, -v107, v117 row_newbcast:1 row_mask:0xf bank_mask:0xf
	v_fmac_f32_dpp v123, -v107, v118 row_newbcast:2 row_mask:0xf bank_mask:0xf
; #define LAS __attribute__((address_space(3)))
; __device__ __forceinline__ void phase_chunk_prep(const Params& p, LAS unsigned char* lds, int wave_s) {
;     ...
;         if (tid < 256) {
;             const int col = tid; float sol[64];
; #pragma unroll
;             for (int i = 0; i < 64; ++i) sol[i] = 0.f;
; #pragma unroll
;             for (int i = 0; i < 64; ++i) {
;                 float s0 = RHS[i * 256 + col], s1 = 0.f, s2 = 0.f, s3 = 0.f;
; #pragma unroll
;                 for (int j4 = 0; j4 < (i + 3) / 4; ++j4) { const f32x4 a = *(const LAS f32x4*)(AM + i * 64 + 4 * j4);
;                     s0 -= a.x * sol[4 * j4]; s1 -= a.y * sol[4 * j4 + 1]; s2 -= a.z * sol[4 * j4 + 2]; s3 -= a.w * sol[4 * j4 + 3]; }
;                 sol[i] = (s0 + s1) + (s2 + s3);
;             }
	v_fmac_f32_dpp v92, -v107, v119 row_newbcast:3 row_mask:0xf bank_mask:0xf
	v_fmac_f32_dpp v123, -v107, v120 row_newbcast:4 row_mask:0xf bank_mask:0xf
	v_fmac_f32_dpp v92, -v107, v121 row_newbcast:5 row_mask:0xf bank_mask:0xf
	v_fmac_f32_dpp v123, -v107, v122 row_newbcast:6 row_mask:0xf bank_mask:0xf
	v_add_f32_e32 v123, v123, v92
	v_mov_b32_e32 v92, 0
	v_fmac_f32_dpp v124, -v108, v116 row_newbcast:0 row_mask:0xf bank_mask:0xf
	v_fmac_f32_dpp v92, -v108, v117 row_newbcast:1 row_mask:0xf bank_mask:0xf
	v_fmac_f32_dpp v124, -v108, v118 row_newbcast:2 row_mask:0xf bank_mask:0xf
	v_fmac_f32_dpp v92, -v108, v119 row_newbcast:3 row_mask:0xf bank_mask:0xf
	v_fmac_f32_dpp v124, -v108, v120 row_newbcast:4 row_mask:0xf bank_mask:0xf
	v_fmac_f32_dpp v92, -v108, v121 row_newbcast:5 row_mask:0xf bank_mask:0xf
	v_fmac_f32_dpp v124, -v108, v122 row_newbcast:6 row_mask:0xf bank_mask:0xf
	v_fmac_f32_dpp v92, -v108, v123 row_newbcast:7 row_mask:0xf bank_mask:0xf
	v_add_f32_e32 v124, v124, v92
	v_mov_b32_e32 v92, 0
	v_fmac_f32_dpp v125, -v109, v116 row_newbcast:0 row_mask:0xf bank_mask:0xf
	v_fmac_f32_dpp v92, -v109, v117 row_newbcast:1 row_mask:0xf bank_mask:0xf
	v_fmac_f32_dpp v125, -v109, v118 row_newbcast:2 row_mask:0xf bank_mask:0xf
	v_fmac_f32_dpp v92, -v109, v119 row_newbcast:3 row_mask:0xf bank_mask:0xf
	v_fmac_f32_dpp v125, -v109, v120 row_newbcast:4 row_mask:0xf bank_mask:0xf
	v_fmac_f32_dpp v92, -v109, v121 row_newbcast:5 row_mask:0xf bank_mask:0xf
	v_fmac_f32_dpp v125, -v109, v122 row_newbcast:6 row_mask:0xf bank_mask:0xf
	v_fmac_f32_dpp v92, -v109, v123 row_newbcast:7 row_mask:0xf bank_mask:0xf
	v_fmac_f32_dpp v125, -v109, v124 row_newbcast:8 row_mask:0xf bank_mask:0xf
	v_add_f32_e32 v125, v125, v92
	v_mov_b32_e32 v92, 0
	v_fmac_f32_dpp v126, -v110, v116 row_newbcast:0 row_mask:0xf bank_mask:0xf
	v_fmac_f32_dpp v92, -v110, v117 row_newbcast:1 row_mask:0xf bank_mask:0xf
	v_fmac_f32_dpp v126, -v110, v118 row_newbcast:2 row_mask:0xf bank_mask:0xf
	v_fmac_f32_dpp v92, -v110, v119 row_newbcast:3 row_mask:0xf bank_mask:0xf
	v_fmac_f32_dpp v126, -v110, v120 row_newbcast:4 row_mask:0xf bank_mask:0xf
	v_fmac_f32_dpp v92, -v110, v121 row_newbcast:5 row_mask:0xf bank_mask:0xf
	v_fmac_f32_dpp v126, -v110, v122 row_newbcast:6 row_mask:0xf bank_mask:0xf
	v_fmac_f32_dpp v92, -v110, v123 row_newbcast:7 row_mask:0xf bank_mask:0xf
	v_fmac_f32_dpp v126, -v110, v124 row_newbcast:8 row_mask:0xf bank_mask:0xf
	v_fmac_f32_dpp v92, -v110, v125 row_newbcast:9 row_mask:0xf bank_mask:0xf
	v_add_f32_e32 v126, v126, v92
	v_mov_b32_e32 v92, 0
	v_fmac_f32_dpp v127, -v111, v116 row_newbcast:0 row_mask:0xf bank_mask:0xf
	v_fmac_f32_dpp v92, -v111, v117 row_newbcast:1 row_mask:0xf bank_mask:0xf
	v_fmac_f32_dpp v127, -v111, v118 row_newbcast:2 row_mask:0xf bank_mask:0xf
	v_fmac_f32_dpp v92, -v111, v119 row_newbcast:3 row_mask:0xf bank_mask:0xf
	v_fmac_f32_dpp v127, -v111, v120 row_newbcast:4 row_mask:0xf bank_mask:0xf
	v_fmac_f32_dpp v92, -v111, v121 row_newbcast:5 row_mask:0xf bank_mask:0xf
	v_fmac_f32_dpp v127, -v111, v122 row_newbcast:6 row_mask:0xf bank_mask:0xf
	v_fmac_f32_dpp v92, -v111, v123 row_newbcast:7 row_mask:0xf bank_mask:0xf
	v_fmac_f32_dpp v127, -v111, v124 row_newbcast:8 row_mask:0xf bank_mask:0xf
	v_fmac_f32_dpp v92, -v111, v125 row_newbcast:9 row_mask:0xf bank_mask:0xf
	v_fmac_f32_dpp v127, -v111, v126 row_newbcast:10 row_mask:0xf bank_mask:0xf
	v_add_f32_e32 v127, v127, v92
	v_mov_b32_e32 v92, 0
	v_fmac_f32_dpp v128, -v112, v116 row_newbcast:0 row_mask:0xf bank_mask:0xf
	v_fmac_f32_dpp v92, -v112, v117 row_newbcast:1 row_mask:0xf bank_mask:0xf
	v_fmac_f32_dpp v128, -v112, v118 row_newbcast:2 row_mask:0xf bank_mask:0xf
	v_fmac_f32_dpp v92, -v112, v119 row_newbcast:3 row_mask:0xf bank_mask:0xf
	v_fmac_f32_dpp v128, -v112, v120 row_newbcast:4 row_mask:0xf bank_mask:0xf
	v_fmac_f32_dpp v92, -v112, v121 row_newbcast:5 row_mask:0xf bank_mask:0xf
	v_fmac_f32_dpp v128, -v112, v122 row_newbcast:6 row_mask:0xf bank_mask:0xf
	v_fmac_f32_dpp v92, -v112, v123 row_newbcast:7 row_mask:0xf bank_mask:0xf
	v_fmac_f32_dpp v128, -v112, v124 row_newbcast:8 row_mask:0xf bank_mask:0xf
; #define LAS __attribute__((address_space(3)))
; __device__ __forceinline__ void phase_chunk_prep(const Params& p, LAS unsigned char* lds, int wave_s) {
;     ...
;         if (tid < 256) {
;             const int col = tid; float sol[64];
; #pragma unroll
;             for (int i = 0; i < 64; ++i) sol[i] = 0.f;
; #pragma unroll
;             for (int i = 0; i < 64; ++i) {
;                 float s0 = RHS[i * 256 + col], s1 = 0.f, s2 = 0.f, s3 = 0.f;
; #pragma unroll
;                 for (int j4 = 0; j4 < (i + 3) / 4; ++j4) { const f32x4 a = *(const LAS f32x4*)(AM + i * 64 + 4 * j4);
;                     s0 -= a.x * sol[4 * j4]; s1 -= a.y * sol[4 * j4 + 1]; s2 -= a.z * sol[4 * j4 + 2]; s3 -= a.w * sol[4 * j4 + 3]; }
;                 sol[i] = (s0 + s1) + (s2 + s3);
;             }
	v_fmac_f32_dpp v92, -v112, v125 row_newbcast:9 row_mask:0xf bank_mask:0xf
	v_fmac_f32_dpp v128, -v112, v126 row_newbcast:10 row_mask:0xf bank_mask:0xf
	v_fmac_f32_dpp v92, -v112, v127 row_newbcast:11 row_mask:0xf bank_mask:0xf
	v_add_f32_e32 v128, v128, v92
	v_mov_b32_e32 v92, 0
	v_fmac_f32_dpp v129, -v113, v116 row_newbcast:0 row_mask:0xf bank_mask:0xf
	v_fmac_f32_dpp v92, -v113, v117 row_newbcast:1 row_mask:0xf bank_mask:0xf
	v_fmac_f32_dpp v129, -v113, v118 row_newbcast:2 row_mask:0xf bank_mask:0xf
	v_fmac_f32_dpp v92, -v113, v119 row_newbcast:3 row_mask:0xf bank_mask:0xf
	v_fmac_f32_dpp v129, -v113, v120 row_newbcast:4 row_mask:0xf bank_mask:0xf
	v_fmac_f32_dpp v92, -v113, v121 row_newbcast:5 row_mask:0xf bank_mask:0xf
	v_fmac_f32_dpp v129, -v113, v122 row_newbcast:6 row_mask:0xf bank_mask:0xf
	v_fmac_f32_dpp v92, -v113, v123 row_newbcast:7 row_mask:0xf bank_mask:0xf
	v_fmac_f32_dpp v129, -v113, v124 row_newbcast:8 row_mask:0xf bank_mask:0xf
	v_fmac_f32_dpp v92, -v113, v125 row_newbcast:9 row_mask:0xf bank_mask:0xf
	v_fmac_f32_dpp v129, -v113, v126 row_newbcast:10 row_mask:0xf bank_mask:0xf
	v_fmac_f32_dpp v92, -v113, v127 row_newbcast:11 row_mask:0xf bank_mask:0xf
	v_fmac_f32_dpp v129, -v113, v128 row_newbcast:12 row_mask:0xf bank_mask:0xf
	v_add_f32_e32 v129, v129, v92
	v_mov_b32_e32 v92, 0
	v_fmac_f32_dpp v130, -v114, v116 row_newbcast:0 row_mask:0xf bank_mask:0xf
	v_fmac_f32_dpp v92, -v114, v117 row_newbcast:1 row_mask:0xf bank_mask:0xf
	v_fmac_f32_dpp v130, -v114, v118 row_newbcast:2 row_mask:0xf bank_mask:0xf
	v_fmac_f32_dpp v92, -v114, v119 row_newbcast:3 row_mask:0xf bank_mask:0xf
	v_fmac_f32_dpp v130, -v114, v120 row_newbcast:4 row_mask:0xf bank_mask:0xf
	v_fmac_f32_dpp v92, -v114, v121 row_newbcast:5 row_mask:0xf bank_mask:0xf
	v_fmac_f32_dpp v130, -v114, v122 row_newbcast:6 row_mask:0xf bank_mask:0xf
	v_fmac_f32_dpp v92, -v114, v123 row_newbcast:7 row_mask:0xf bank_mask:0xf
	v_fmac_f32_dpp v130, -v114, v124 row_newbcast:8 row_mask:0xf bank_mask:0xf
	v_fmac_f32_dpp v92, -v114, v125 row_newbcast:9 row_mask:0xf bank_mask:0xf
	v_fmac_f32_dpp v130, -v114, v126 row_newbcast:10 row_mask:0xf bank_mask:0xf
	v_fmac_f32_dpp v92, -v114, v127 row_newbcast:11 row_mask:0xf bank_mask:0xf
	v_fmac_f32_dpp v130, -v114, v128 row_newbcast:12 row_mask:0xf bank_mask:0xf
	v_fmac_f32_dpp v92, -v114, v129 row_newbcast:13 row_mask:0xf bank_mask:0xf
	v_add_f32_e32 v130, v130, v92
	v_mov_b32_e32 v92, 0
	v_fmac_f32_dpp v131, -v115, v116 row_newbcast:0 row_mask:0xf bank_mask:0xf
	v_fmac_f32_dpp v92, -v115, v117 row_newbcast:1 row_mask:0xf bank_mask:0xf
	v_fmac_f32_dpp v131, -v115, v118 row_newbcast:2 row_mask:0xf bank_mask:0xf
	v_fmac_f32_dpp v92, -v115, v119 row_newbcast:3 row_mask:0xf bank_mask:0xf
	v_fmac_f32_dpp v131, -v115, v120 row_newbcast:4 row_mask:0xf bank_mask:0xf
	v_fmac_f32_dpp v92, -v115, v121 row_newbcast:5 row_mask:0xf bank_mask:0xf
	v_fmac_f32_dpp v131, -v115, v122 row_newbcast:6 row_mask:0xf bank_mask:0xf
	v_fmac_f32_dpp v92, -v115, v123 row_newbcast:7 row_mask:0xf bank_mask:0xf
	v_fmac_f32_dpp v131, -v115, v124 row_newbcast:8 row_mask:0xf bank_mask:0xf
	v_fmac_f32_dpp v92, -v115, v125 row_newbcast:9 row_mask:0xf bank_mask:0xf
	v_fmac_f32_dpp v131, -v115, v126 row_newbcast:10 row_mask:0xf bank_mask:0xf
	v_fmac_f32_dpp v92, -v115, v127 row_newbcast:11 row_mask:0xf bank_mask:0xf
	v_fmac_f32_dpp v131, -v115, v128 row_newbcast:12 row_mask:0xf bank_mask:0xf
	v_fmac_f32_dpp v92, -v115, v129 row_newbcast:13 row_mask:0xf bank_mask:0xf
	v_fmac_f32_dpp v131, -v115, v130 row_newbcast:14 row_mask:0xf bank_mask:0xf
	v_add_f32_e32 v131, v131, v92
	ds_write_b32 v87, v116
	ds_write_b32 v87, v117 offset:80
	ds_write_b32 v87, v118 offset:160
	ds_write_b32 v87, v119 offset:240
	ds_write_b32 v87, v120 offset:320
	ds_write_b32 v87, v121 offset:400
	ds_write_b32 v87, v122 offset:480
	ds_write_b32 v87, v123 offset:560
	ds_write_b32 v87, v124 offset:640
	ds_write_b32 v87, v125 offset:720
	ds_write_b32 v87, v126 offset:800
	ds_write_b32 v87, v127 offset:880
	ds_write_b32 v87, v128 offset:960
	ds_write_b32 v87, v129 offset:1040
	ds_write_b32 v87, v130 offset:1120
	ds_write_b32 v87, v131 offset:1200
